# FA loops back edge rotated (7.11): has-next / buffer-select / skip test and K-fragment LDS address VALU moved in front of the per-tile barrier in MLA, MOBA, SLC, DSA; v16 otherwise
# baseline (speedup 1.0000x reference)
; __device__ __forceinline__ void fa_mixer_phase(Frame& F, int l) {
;     ...
;     for (;;) {
;         const int u = fa_ticket(F, F.ctl + CW_QUEUE + 64 * l);
;         if (u >= 512) break;
;         const int qb = 31 - (u >> 4), type = (u >> 2) & 3, h = u & 3, P0 = qb * 256;
;         if (!((FA_MASK >> type) & 1)) continue;
;         fa::UnitArgs U; U.P0 = P0; U.j_lo = 0; U.j_hi = (P0 + 255) / 64 + 1; U.KR = nullptr; U.mk = nullptr; U.gate = nullptr; U.gidx = 0; U.ocmp = nullptr; U.epi = 0; U.old = DM;
;         if (type == 0) {
;             U.Q = (const h16*)(ws + WS_Q192) + ((size_t)h * S + P0) * 192; U.qld = 192; U.K = (const h16*)(ws + WS_KN + (size_t)h * HEADBUF); U.KR = (const h16*)(ws + WS_BKR); U.V = (const h16*)(ws + WS_BV + (size_t)h * HEADBUF);
;             U.O = (h16*)(ws + WS_OMIX) + (size_t)P0 * DM + 512 + h * 128;
;             fa::run_unit<fa::K_MLA>(lds, U, F.tid);
;         } else if (type == 1) {
;             U.Q = (const h16*)(ws + WS_CQROPE + (size_t)h * HEADBUF) + (size_t)P0 * 128; U.qld = 128; U.K = (const h16*)(ws + WS_KSLC); U.V = (const h16*)(ws + WS_VSLC);
;             U.O = (h16*)(ws + WS_OMIX) + (size_t)P0 * DM + 1024 + h * 128; U.mk = ws + WS_NSAMASK; U.gate = (const float*)(ws + WS_SMALL); U.gidx = h * 3 + 1; U.epi = 2;
;             fa::run_unit<fa::K_SLC>(lds, U, F.tid);
;             U.K = (const h16*)(ws + WS_KWIN); U.V = (const h16*)(ws + WS_VWIN); U.j_lo = P0 >= 511 ? (P0 - 511) / 64 : 0; U.gidx = h * 3 + 2; U.epi = 2;
;             fa::run_unit<fa::K_WIN>(lds, U, F.tid);
;         } else if (type == 2) {
;             U.Q = (const h16*)(ws + WS_AQ + (size_t)h * HEADBUF) + (size_t)P0 * 128; U.qld = 128; U.K = (const h16*)(ws + WS_AK + (size_t)h * HEADBUF); U.V = (const h16*)(ws + WS_AV + (size_t)h * HEADBUF);
;             U.O = (h16*)(ws + WS_OMIX) + (size_t)P0 * DM + h * 128; U.mk = (const int*)(ws + WS_MOBASEL) + h * 4;
;             fa::run_unit<fa::K_MOBA>(lds, U, F.tid);
;         } else {
;             U.Q = (const h16*)(ws + WS_DQ + (size_t)h * HEADBUF) + (size_t)P0 * 128; U.qld = 128; U.K = (const h16*)(ws + WS_DK + (size_t)h * HEADBUF); U.V = (const h16*)(ws + WS_DV + (size_t)h * HEADBUF);
;             U.O = (h16*)(ws + WS_OMIX) + (size_t)P0 * DM + 1536 + h * 128; U.mk = ws + WS_DSAMASK;
;             fa::run_unit<fa::K_DSA>(lds, U, F.tid);
.LBB0_4927:
	s_or_b64 exec, exec, s[0:1]
	v_mov_b32_e32 v1, s83
	s_waitcnt vmcnt(0) lgkmcnt(0)
	s_barrier
	ds_read_b32 v1, v1
	s_movk_i32 s0, 0x1ff
	s_waitcnt lgkmcnt(0)
	s_barrier
	v_cmp_lt_i32_e32 vcc, s0, v1
	v_readfirstlane_b32 s2, v1
	s_mov_b64 s[0:1], -1
	s_cbranch_vccnz .LBB0_4922
	s_lshl_b32 s0, s2, 4
	s_and_b32 s12, s0, 0xffffff00
	s_sub_i32 s0, 0x1fc0, s12
	s_lshr_b32 s15, s0, 6
	s_bfe_u32 s10, s2, 0x20002
	s_and_b32 s14, s2, 3
	s_sub_i32 s2, 0x1f00, s12
	s_add_i32 s13, s15, 1
	s_cmp_lt_i32 s10, 2
	s_mov_b64 s[0:1], -1
	s_cbranch_scc1 .LBB0_4968
	s_cmp_gt_i32 s10, 2
	s_cbranch_scc0 .LBB0_4945
	s_lshl_b32 s8, s14, 21
	v_readlane_b32 s0, v253, 60
	s_add_u32 s6, s0, s8
	v_readlane_b32 s0, v253, 61
	s_addc_u32 s7, s0, 0
	s_lshl_b64 s[0:1], s[2:3], 8
	s_add_u32 s0, s6, s0
	s_addc_u32 s1, s7, s1
	v_readlane_b32 s6, v253, 62
	v_mov_b32_e32 v1, v0
	s_add_u32 s6, s6, s8
	v_readlane_b32 s7, v253, 63
	s_addc_u32 s7, s7, 0
	v_ashrrev_i32_e32 v162, 4, v1
	v_readlane_b32 s9, v251, 58
	v_lshlrev_b32_e32 v16, 3, v1
	v_add_u32_e32 v6, 32, v162
	v_ashrrev_i32_e32 v163, 31, v162
	s_add_u32 s8, s9, s8
	v_readlane_b32 s9, v251, 59
	v_and_b32_e32 v2, 0x78, v16
	v_lshlrev_b64 v[8:9], 8, v[162:163]
	v_ashrrev_i32_e32 v7, 31, v6
	s_addc_u32 s9, s9, 0
	v_lshlrev_b32_e32 v4, 1, v2
	v_lshl_add_u64 v[10:11], s[6:7], 0, v[8:9]
	v_mov_b32_e32 v5, v3
	v_lshlrev_b64 v[12:13], 8, v[6:7]
	v_lshl_add_u64 v[10:11], v[10:11], 0, v[4:5]
	v_lshl_add_u64 v[14:15], s[6:7], 0, v[12:13]
	v_lshl_add_u64 v[8:9], s[8:9], 0, v[8:9]
	v_lshl_add_u64 v[14:15], v[14:15], 0, v[4:5]
	global_load_dwordx4 v[114:117], v[10:11], off
	global_load_dwordx4 v[118:121], v[14:15], off
	v_lshl_add_u64 v[8:9], v[8:9], 0, v[4:5]
	v_lshl_add_u64 v[10:11], s[8:9], 0, v[12:13]
	v_lshl_add_u64 v[10:11], v[10:11], 0, v[4:5]
	global_load_dwordx4 v[122:125], v[8:9], off
	global_load_dwordx4 v[126:129], v[10:11], off
	v_readfirstlane_b32 s11, v1
	s_ashr_i32 s16, s11, 6
	v_and_b32_e32 v172, 31, v1
	s_lshl_b32 s11, s16, 5
	v_or_b32_e32 v8, s11, v172
	s_add_i32 s17, s11, s2
	v_ashrrev_i32_e32 v9, 31, v8
	v_bfe_u32 v163, v1, 5, 1
	v_or_b32_e32 v10, s17, v172
	v_lshlrev_b64 v[8:9], 8, v[8:9]
	v_lshlrev_b32_e32 v2, 4, v163
	v_ashrrev_i32_e32 v11, 31, v10
	v_lshl_add_u64 v[8:9], s[0:1], 0, v[8:9]
	v_lshlrev_b64 v[10:11], 10, v[10:11]
	v_lshl_add_u64 v[8:9], v[8:9], 0, v[2:3]
	v_lshl_add_u64 v[12:13], s[84:85], 0, v[10:11]
	global_load_dwordx4 v[130:133], v[8:9], off
	global_load_dwordx4 v[134:137], v[8:9], off offset:32
	global_load_dwordx4 v[138:141], v[8:9], off offset:64
	global_load_dwordx4 v[142:145], v[8:9], off offset:96
	global_load_dwordx2 v[164:165], v[12:13], off
	global_load_dwordx4 v[146:149], v[8:9], off offset:128
	global_load_dwordx4 v[150:153], v[8:9], off offset:160
	global_load_dwordx4 v[154:157], v[8:9], off offset:192
	global_load_dwordx4 v[158:161], v[8:9], off offset:224
	v_and_b32_e32 v7, 0xfffff0, v162
	v_lshlrev_b32_e32 v14, 1, v162
	v_and_or_b32 v7, v14, 8, v7
	v_and_b32_e32 v13, 0xfffff0, v6
	v_lshlrev_b32_e32 v6, 1, v6
	v_lshrrev_b32_e32 v15, 1, v162
	v_bfe_u32 v8, v16, 5, 2
	v_and_b32_e32 v9, 3, v162
	v_lshrrev_b32_e32 v7, 1, v7
	v_and_or_b32 v6, v6, 8, v13
	v_and_or_b32 v9, v15, 4, v9
	v_or_b32_e32 v7, v7, v8
	v_lshrrev_b32_e32 v6, 1, v6
	v_lshlrev_b32_e32 v9, 6, v9
	v_and_b32_e32 v13, 48, v4
	v_lshlrev_b32_e32 v7, 9, v7
	v_or_b32_e32 v6, v6, v8
	v_lshlrev_b32_e32 v12, 8, v162
	v_bitop3_b32 v14, v4, v1, s50 bitop3:0x78
	v_lshlrev_b32_e32 v6, 9, v6
	v_or3_b32 v177, v7, v9, v13
	v_add3_u32 v176, 0, v14, v12
	s_mul_i32 s0, s16, 0x180
	v_or3_b32 v178, v6, v9, v13
	v_add_u32_e32 v6, 0, v177
	s_add_i32 s0, s0, 0
	v_add_u32_e32 v7, 0, v178
	s_waitcnt vmcnt(0)
	v_lshlrev_b32_e32 v175, 4, v1
	v_and_b32_e32 v173, 63, v1
	s_add_i32 s22, s0, 0x14000
	v_lshl_add_u64 v[166:167], s[6:7], 0, v[4:5]
	s_movk_i32 s6, 0x118
	v_bitop3_b32 v181, v2, v175, s50 bitop3:0x78
	v_mov_b32_e32 v17, v3
	v_lshl_add_u64 v[168:169], s[8:9], 0, v[4:5]
	v_and_b32_e32 v98, 15, v0
	v_bfe_u32 v99, v0, 4, 3
	v_xor_b32_e32 v100, v98, v99
	v_sub_u32_e32 v100, v100, v98
	v_lshlrev_b32_e32 v100, 4, v100
	v_ashrrev_i32_e32 v101, 31, v100
	v_lshl_add_u64 v[166:167], v[166:167], 0, v[100:101]
	v_lshrrev_b32_e32 v102, 7, v0
	v_bfe_u32 v103, v0, 2, 3
	v_lshl_or_b32 v102, v102, 3, v103
	v_and_b32_e32 v104, 4, v102
	v_lshlrev_b32_e32 v104, 1, v104
	v_and_b32_e32 v105, 8, v102
	v_lshrrev_b32_e32 v105, 1, v105
	v_and_b32_e32 v102, 0x33, v102
	v_or3_b32 v102, v102, v104, v105
	v_lshrrev_b32_e32 v103, 4, v0
	v_sub_u32_e32 v102, v102, v103
	v_lshlrev_b32_e32 v102, 8, v102
	v_bfe_u32 v103, v0, 5, 2
	v_lshlrev_b32_e32 v103, 6, v103
	v_and_b32_e32 v104, 3, v0
	v_lshl_or_b32 v103, v104, 4, v103
	v_lshlrev_b32_e32 v104, 4, v98
	v_sub_u32_e32 v103, v103, v104
	v_add_u32_e32 v102, v102, v103
	v_ashrrev_i32_e32 v103, 31, v102
	v_lshl_add_u64 v[168:169], v[168:169], 0, v[102:103]
	s_waitcnt vmcnt(12)
; #define FA_SBAR() __builtin_amdgcn_sched_barrier(0)
; #define FA_WRITET(bf) do { *(LAS half8*)(lds + OFF_K + (bf) * SHM_K + kws) = st_k0; *(LAS half8*)(lds + OFF_K + (bf) * SHM_K + kws + 32 * 256) = st_k1; \
;         *(LAS half8*)(lds + OFF_V + (bf) * SHM_V + vst0) = st_v0; *(LAS half8*)(lds + OFF_V + (bf) * SHM_V + vst1) = st_v1; \
;         if constexpr (MLA) *(LAS half8*)(lds + OFF_KR + (bf) * SHM_KR + krw) = st_kr; } while (0)
; template <int KIND>
; __device__ __forceinline__ void run_unit(LAS char* lds, const UnitArgs& U, int tid_in) {
;     ...
;     float m_reg = -1e30f, l_reg = 0.f; f32x16 o[4];
; #pragma unroll
;     for (int d = 0; d < 4; ++d)
; #pragma unroll
;         for (int r = 0; r < 16; ++r) o[d][r] = 0.f;
;     FA_LOADT(U.j_lo); asm volatile("s_waitcnt vmcnt(0)" ::: "memory"); FA_WRITET(0); dm_lo = dn_lo; dm_hi = dn_hi;
;     __syncthreads();
;     f32x16 pA0, pA1; float mnA, alA; half8 pa0, pa1, pa2, pa3;
;     ...
;     for (int t = 0; t < NT; ++t) {
;         if (t + 1 < NT) FA_LOADT(U.j_lo + t + 1);
;         FA_SBAR();
;         FA_STEP(t);
;         FA_SBAR();
;         if (t + 1 < NT) { asm volatile("s_waitcnt vmcnt(0)" ::: "memory"); FA_WRITET((t + 1) & 1); dm_lo = dn_lo; dm_hi = dn_hi; }
;         __syncthreads();
;     }
	ds_write_b128 v176, v[114:117] offset:32768
	s_waitcnt vmcnt(11)
	ds_write_b128 v176, v[118:121] offset:40960
	s_waitcnt vmcnt(10)
	ds_write_b128 v6, v[122:125]
	s_waitcnt vmcnt(9)
	ds_write_b128 v7, v[126:129]
	v_lshlrev_b32_e32 v6, 1, v1
	v_and_b32_e32 v6, 32, v6
	v_and_b32_e32 v1, 0x70, v175
	v_bitop3_b32 v182, v2, v1, 32 bitop3:0x36
	v_bitop3_b32 v183, v2, v1, 64 bitop3:0x36
	v_bitop3_b32 v184, v2, v1, s77 bitop3:0x36
	v_add_u32_e32 v1, s22, v2
	v_and_or_b32 v2, v16, s6, v6
	v_readlane_b32 s6, v255, 2
	v_and_b32_e32 v7, 0xc0, v175
	v_readlane_b32 s7, v255, 3
	v_mov_b32_e32 v16, v3
	v_add3_u32 v185, v7, 0, v2
	v_lshl_add_u64 v[170:171], s[6:7], 0, v[10:11]
	v_mov_b32_e32 v2, v3
	v_mov_b32_e32 v4, v3
	v_mov_b32_e32 v6, v3
	v_mov_b32_e32 v7, v3
	v_mov_b32_e32 v8, v3
	v_mov_b32_e32 v9, v3
	v_mov_b32_e32 v10, v3
	v_mov_b32_e32 v11, v3
	v_mov_b32_e32 v12, v3
	v_mov_b32_e32 v13, v3
	v_mov_b32_e32 v14, v3
	v_mov_b32_e32 v15, v3
	v_mov_b64_e32 v[32:33], v[16:17]
	v_mov_b64_e32 v[48:49], v[16:17]
	v_mov_b64_e32 v[64:65], v[16:17]
	v_mov_b64_e32 v[80:81], v[16:17]
	s_or_b32 s17, s17, 31
	v_lshl_add_u32 v180, v172, 8, 0
	v_lshlrev_b32_e32 v174, 2, v163
	v_cmp_gt_u32_e64 s[0:1], 32, v173
	v_lshl_add_u32 v179, v172, 2, s22
	s_mov_b32 s22, 0
	v_mov_b32_e32 v187, 0
	v_mov_b32_e32 v186, 0xf149f2ca
	s_movk_i32 s23, 0x4000
	v_mov_b64_e32 v[30:31], v[14:15]
	v_mov_b64_e32 v[28:29], v[12:13]
	v_mov_b64_e32 v[26:27], v[10:11]
	v_mov_b64_e32 v[24:25], v[8:9]
	v_mov_b64_e32 v[22:23], v[6:7]
	v_mov_b64_e32 v[20:21], v[4:5]
	v_mov_b64_e32 v[18:19], v[2:3]
	v_mov_b64_e32 v[46:47], v[14:15]
	v_mov_b64_e32 v[44:45], v[12:13]
	v_mov_b64_e32 v[42:43], v[10:11]
	v_mov_b64_e32 v[40:41], v[8:9]
	v_mov_b64_e32 v[38:39], v[6:7]
	v_mov_b64_e32 v[36:37], v[4:5]
	v_mov_b64_e32 v[34:35], v[2:3]
	v_mov_b64_e32 v[62:63], v[14:15]
	v_mov_b64_e32 v[60:61], v[12:13]
	v_mov_b64_e32 v[58:59], v[10:11]
	v_mov_b64_e32 v[56:57], v[8:9]
	v_mov_b64_e32 v[54:55], v[6:7]
	v_mov_b64_e32 v[52:53], v[4:5]
	v_mov_b64_e32 v[50:51], v[2:3]
	v_mov_b64_e32 v[78:79], v[14:15]
	v_mov_b64_e32 v[76:77], v[12:13]
	v_mov_b64_e32 v[74:75], v[10:11]
	v_mov_b64_e32 v[72:73], v[8:9]
	v_mov_b64_e32 v[70:71], v[6:7]
	v_mov_b64_e32 v[68:69], v[4:5]
	v_mov_b64_e32 v[66:67], v[2:3]
	s_waitcnt vmcnt(4)
	v_mov_b32_e32 v4, v164
	v_mov_b32_e32 v5, v165
	s_mov_b32 s24, 0
	s_branch .Ldsa_rot
.LBB0_4931:
	s_add_i32 s24, s24, 1
	s_add_i32 s22, s22, 64
	s_addk_i32 s23, 0x4000
	v_lshl_add_u64 v[170:171], v[170:171], 0, 8
.Ldsa_rot:
	s_cmp_lt_u32 s24, s15
	s_cselect_b64 s[6:7], -1, 0
	s_and_b32 s8, s24, 1
	v_mov_b32_e32 v2, s8
	s_cmp_gt_i32 s22, s17
	s_cselect_b64 vcc, -1, 0
	v_lshlrev_b32_e32 v2, 14, v2
	v_add_u32_e32 v6, v180, v2
	v_add_u32_e32 v196, v6, v181
	v_add_u32_e32 v197, v6, v182
	v_add_u32_e32 v208, v6, v183
	v_add_u32_e32 v209, v6, v184
	s_cmp_eq_u32 s13, s24
	s_waitcnt lgkmcnt(0)
	s_barrier
	s_cbranch_scc1 .LBB0_4942
	s_cbranch_vccnz .Ldsa_skipq
	ds_read_b128 v[6:9], v196 offset:32768
	ds_read_b128 v[10:13], v196 offset:40960
	ds_read_b128 v[14:17], v197 offset:32768
	ds_read_b128 v[188:191], v197 offset:40960
	ds_read_b128 v[192:195], v208 offset:32768
	ds_read_b128 v[204:207], v208 offset:40960
	ds_read_b128 v[220:223], v209 offset:32768
	ds_read_b128 v[224:227], v209 offset:40960
	s_and_b64 vcc, exec, s[6:7]
	s_cbranch_vccz .Ldsa_q_nold
	v_readfirstlane_b32 vcc_hi, v0
	s_and_b32 vcc_lo, s23, 0x4000
	s_lshr_b32 vcc_hi, vcc_hi, 6
	s_lshl_b32 vcc_hi, vcc_hi, 10
	s_add_i32 vcc_lo, vcc_lo, vcc_hi
	v_add_u32_e32 v98, s22, v162
	v_add_u32_e32 v100, 64, v98
	v_ashrrev_i32_e32 v101, 31, v100
	v_add_u32_e32 v104, 0x60, v98
	v_lshlrev_b64 v[100:101], 8, v[100:101]
	v_ashrrev_i32_e32 v105, 31, v104
	s_add_i32 m0, vcc_lo, 0x8000
	v_lshl_add_u64 v[102:103], v[166:167], 0, v[100:101]
	v_lshlrev_b64 v[104:105], 8, v[104:105]
	global_load_lds_dwordx4 v[102:103], off
	s_add_i32 m0, vcc_lo, 0xa000
	v_lshl_add_u64 v[106:107], v[166:167], 0, v[104:105]
	v_lshl_add_u64 v[100:101], v[168:169], 0, v[100:101]
	global_load_lds_dwordx4 v[106:107], off
	s_mov_b32 m0, vcc_lo
	v_lshl_add_u64 v[102:103], v[168:169], 0, v[104:105]
	s_nop 0
	global_load_lds_dwordx4 v[100:101], off
	s_add_i32 m0, vcc_lo, 0x2000
	s_nop 0
	global_load_lds_dwordx4 v[102:103], off
	s_nop 0
	global_load_dwordx2 v[4:5], v[170:171], off

; template <int KIND>
; __device__ __forceinline__ void run_unit(LAS char* lds, const UnitArgs& U, int tid_in) {
;     ...
;     const int wid = __builtin_amdgcn_readfirstlane(tid >> 6), lane = tid & 63, r32 = lane & 31, hi = lane >> 5;
;     const int sr = tid >> 4, sc = (tid & 15) * 8;
;     const int qlo = U.P0 + wid * 32, rowpos = qlo + r32;
;     const float sc_ = MLA ? SC192 : SC128; const float C2 = 1.4426950408889634f * sc_;
;     LAS float* wsf = (LAS float*)(lds + OFF_WS) + wid * 96; LAS float* li_l = wsf; LAS float* al_l = wsf + 32; LAS float* g_l = wsf + 64;
;     half8 qr[MLA ? 12 : 8];
;     { const h16* qp = U.Q + (size_t)(wid * 32 + r32) * U.qld + hi * 8;
; #pragma unroll
;       for (int d0 = 0; d0 < (MLA ? 12 : 8); ++d0) qr[d0] = *(const half8*)(qp + d0 * 16); }
;     unsigned mb0 = 0, mb1 = 0, mb2 = 0, mb3 = 0;
;     if constexpr (KIND == K_MOBA) { const int* s = (const int*)U.mk + (size_t)rowpos * 16;
; #pragma unroll
;         for (int i = 0; i < 3; ++i) { const int b = s[i]; if (b >= 0) mb0 |= 1u << b; } }
;     if constexpr (KIND == K_SLC) { const u32x4 m = *(const u32x4*)((const unsigned*)U.mk + (size_t)rowpos * 4); mb0 = m[0]; mb1 = m[1]; mb2 = m[2]; mb3 = m[3]; }
;     const int nvis_row = rowpos >= 31 ? ((rowpos - 31) >> 4) + 1 : 0;
;     const int NT = U.j_hi - U.j_lo;
;     half8 st_k0, st_k1, st_v0, st_v1, st_kr; unsigned dm_lo = 0, dm_hi = 0, dn_lo = 0, dn_hi = 0;
;     const int kws = FA_KSWZ(sr, sc * 2), vst0 = v_st(sr, sc), vst1 = v_st(32 + sr, sc), krw = FA_KRSWZ(tid >> 3, (tid & 7) * 16);
;     const int vb0 = (int)(unsigned)(size_t)(lds + OFF_V) + v_rd_base(lane);
;     ...
;     float m_reg = -1e30f, l_reg = 0.f; f32x16 o[4];
; #pragma unroll
;     for (int d = 0; d < 4; ++d)
; #pragma unroll
;         for (int r = 0; r < 16; ++r) o[d][r] = 0.f;
;     FA_LOADT(U.j_lo); asm volatile("s_waitcnt vmcnt(0)" ::: "memory"); FA_WRITET(0); dm_lo = dn_lo; dm_hi = dn_hi;
; __device__ __forceinline__ void fa_mixer_phase(Frame& F, int l) {
;     ...
;         } else if (type == 2) {
;             U.Q = (const h16*)(ws + WS_AQ + (size_t)h * HEADBUF) + (size_t)P0 * 128; U.qld = 128; U.K = (const h16*)(ws + WS_AK + (size_t)h * HEADBUF); U.V = (const h16*)(ws + WS_AV + (size_t)h * HEADBUF);
;             U.O = (h16*)(ws + WS_OMIX) + (size_t)P0 * DM + h * 128; U.mk = (const int*)(ws + WS_MOBASEL) + h * 4;
;             fa::run_unit<fa::K_MOBA>(lds, U, F.tid);
.LBB0_4945:
	s_and_b64 vcc, exec, s[0:1]
	s_cbranch_vccz .LBB0_4967
	s_lshl_b32 s8, s14, 21
	v_readlane_b32 s0, v253, 38
	s_add_u32 s6, s0, s8
	v_readlane_b32 s0, v253, 39
	s_addc_u32 s7, s0, 0
	s_lshl_b64 s[0:1], s[2:3], 8
	s_add_u32 s0, s6, s0
	s_addc_u32 s1, s7, s1
	v_readlane_b32 s6, v253, 13
	s_add_u32 s6, s6, s8
	v_readlane_b32 s7, v253, 14
	s_addc_u32 s7, s7, 0
	v_readlane_b32 s9, v252, 4
	s_add_u32 s8, s9, s8
	v_readlane_b32 s9, v252, 5
	s_addc_u32 s9, s9, 0
	s_lshl_b32 s11, s14, 4
	v_readlane_b32 s16, v253, 36
	v_mov_b32_e32 v1, v0
	v_readlane_b32 s17, v253, 37
	s_add_u32 s22, s16, s11
	s_addc_u32 s23, s17, 0
	v_readfirstlane_b32 s11, v1
	s_ashr_i32 s11, s11, 6
	s_lshl_b32 s16, s11, 5
	v_and_b32_e32 v220, 31, v1
	s_add_i32 s17, s16, s2
	v_ashrrev_i32_e32 v204, 4, v1
	v_lshlrev_b32_e32 v7, 3, v1
	v_or_b32_e32 v4, s17, v220
	v_ashrrev_i32_e32 v205, 31, v204
	v_ashrrev_i32_e32 v5, 31, v4
	v_and_b32_e32 v2, 0x78, v7
	v_lshlrev_b64 v[12:13], 8, v[204:205]
	v_lshlrev_b64 v[4:5], 6, v[4:5]
	v_lshlrev_b32_e32 v8, 1, v2
	v_add_u32_e32 v10, 32, v204
	v_lshl_add_u64 v[14:15], s[6:7], 0, v[12:13]
	v_mov_b32_e32 v9, v3
	v_lshl_add_u64 v[4:5], s[22:23], 0, v[4:5]
	v_lshl_add_u64 v[14:15], v[14:15], 0, v[8:9]
	v_ashrrev_i32_e32 v11, 31, v10
	global_load_dwordx3 v[4:6], v[4:5], off
	v_lshl_add_u64 v[12:13], s[8:9], 0, v[12:13]
	global_load_dwordx4 v[146:149], v[14:15], off
	v_lshlrev_b64 v[14:15], 8, v[10:11]
	v_lshl_add_u64 v[16:17], s[6:7], 0, v[14:15]
	v_lshl_add_u64 v[16:17], v[16:17], 0, v[8:9]
	v_lshl_add_u64 v[12:13], v[12:13], 0, v[8:9]
	global_load_dwordx4 v[150:153], v[16:17], off
	global_load_dwordx4 v[154:157], v[12:13], off
	v_lshl_add_u64 v[12:13], s[8:9], 0, v[14:15]
	v_lshl_add_u64 v[12:13], v[12:13], 0, v[8:9]
	global_load_dwordx4 v[158:161], v[12:13], off
	v_and_b32_e32 v11, 0xfffff0, v204
	v_lshlrev_b32_e32 v12, 1, v204
	v_lshrrev_b32_e32 v13, 1, v204
	v_and_b32_e32 v15, 3, v204
	v_and_or_b32 v11, v12, 8, v11
	v_and_or_b32 v12, v13, 4, v15
	v_and_b32_e32 v13, 0xfffff0, v10
	v_lshlrev_b32_e32 v15, 1, v10
	v_or_b32_e32 v10, s16, v220
	v_lshrrev_b32_e32 v18, 1, v11
	v_ashrrev_i32_e32 v11, 31, v10
	v_bfe_u32 v205, v1, 5, 1
	v_lshlrev_b64 v[10:11], 8, v[10:11]
	v_lshlrev_b32_e32 v2, 4, v205
	v_lshl_add_u64 v[10:11], s[0:1], 0, v[10:11]
	v_lshl_add_u64 v[10:11], v[10:11], 0, v[2:3]
	global_load_dwordx4 v[162:165], v[10:11], off
	global_load_dwordx4 v[166:169], v[10:11], off offset:32
	global_load_dwordx4 v[170:173], v[10:11], off offset:64
	global_load_dwordx4 v[174:177], v[10:11], off offset:96
	global_load_dwordx4 v[178:181], v[10:11], off offset:128
	global_load_dwordx4 v[182:185], v[10:11], off offset:160
	global_load_dwordx4 v[186:189], v[10:11], off offset:192
	global_load_dwordx4 v[190:193], v[10:11], off offset:224
	v_and_or_b32 v10, v15, 8, v13
	v_bfe_u32 v14, v7, 5, 2
	v_lshrrev_b32_e32 v10, 1, v10
	v_or_b32_e32 v10, v10, v14
	v_lshlrev_b32_e32 v12, 6, v12
	v_and_b32_e32 v11, 48, v8
	v_or_b32_e32 v13, v18, v14
	v_lshlrev_b32_e32 v10, 9, v10
	v_lshlrev_b32_e32 v13, 9, v13
	v_or3_b32 v225, v10, v12, v11
	v_or3_b32 v224, v13, v12, v11
	v_lshlrev_b32_e32 v16, 8, v204
	v_bitop3_b32 v17, v8, v1, s50 bitop3:0x78
	v_add3_u32 v228, 0, v17, v16
	s_mul_i32 s0, s11, 0x180
	s_waitcnt vmcnt(0)
	s_add_i32 s0, s0, 0
	v_lshlrev_b32_e32 v223, 4, v1
	v_and_b32_e32 v221, 63, v1
	s_add_i32 s25, s0, 0x14000
	v_lshl_add_u64 v[206:207], s[6:7], 0, v[8:9]
	s_movk_i32 s6, 0x118
	v_bitop3_b32 v230, v2, v223, s50 bitop3:0x78
	v_lshlrev_b32_e32 v222, 2, v205
	v_mov_b32_e32 v16, v3
	v_mov_b32_e32 v17, v3
	v_lshl_add_u64 v[208:209], s[8:9], 0, v[8:9]
	v_and_b32_e32 v114, 15, v0
	v_bfe_u32 v115, v0, 4, 3
	v_xor_b32_e32 v116, v114, v115
	v_sub_u32_e32 v116, v116, v114
	v_lshlrev_b32_e32 v116, 4, v116
	v_ashrrev_i32_e32 v117, 31, v116
	v_lshl_add_u64 v[206:207], v[206:207], 0, v[116:117]
	v_lshrrev_b32_e32 v118, 7, v0
	v_bfe_u32 v119, v0, 2, 3
	v_lshl_or_b32 v118, v118, 3, v119
	v_and_b32_e32 v120, 4, v118
	v_lshlrev_b32_e32 v120, 1, v120
	v_and_b32_e32 v121, 8, v118
	v_lshrrev_b32_e32 v121, 1, v121
	v_and_b32_e32 v118, 0x33, v118
	v_or3_b32 v118, v118, v120, v121
	v_lshrrev_b32_e32 v119, 4, v0
	v_sub_u32_e32 v118, v118, v119
	v_lshlrev_b32_e32 v118, 8, v118
	v_bfe_u32 v119, v0, 5, 2
	v_lshlrev_b32_e32 v119, 6, v119
	v_and_b32_e32 v120, 3, v0
	v_lshl_or_b32 v119, v120, 4, v119
	v_lshlrev_b32_e32 v120, 4, v114
	v_sub_u32_e32 v119, v119, v120
	v_add_u32_e32 v118, v118, v119
	v_ashrrev_i32_e32 v119, 31, v118
	v_lshl_add_u64 v[208:209], v[208:209], 0, v[118:119]
	v_mov_b32_e32 v8, v3
	s_waitcnt vmcnt(11)
; #define FA_SBAR() __builtin_amdgcn_sched_barrier(0)
; #define FA_WRITET(bf) do { *(LAS half8*)(lds + OFF_K + (bf) * SHM_K + kws) = st_k0; *(LAS half8*)(lds + OFF_K + (bf) * SHM_K + kws + 32 * 256) = st_k1; \
;         *(LAS half8*)(lds + OFF_V + (bf) * SHM_V + vst0) = st_v0; *(LAS half8*)(lds + OFF_V + (bf) * SHM_V + vst1) = st_v1; \
;         if constexpr (MLA) *(LAS half8*)(lds + OFF_KR + (bf) * SHM_KR + krw) = st_kr; } while (0)
; template <int KIND>
; __device__ __forceinline__ void run_unit(LAS char* lds, const UnitArgs& U, int tid_in) {
;     ...
;     if constexpr (KIND == K_MOBA) { const int* s = (const int*)U.mk + (size_t)rowpos * 16;
; #pragma unroll
;         for (int i = 0; i < 3; ++i) { const int b = s[i]; if (b >= 0) mb0 |= 1u << b; } }
;     ...
;     float m_reg = -1e30f, l_reg = 0.f; f32x16 o[4];
; #pragma unroll
;     for (int d = 0; d < 4; ++d)
; #pragma unroll
;         for (int r = 0; r < 16; ++r) o[d][r] = 0.f;
;     FA_LOADT(U.j_lo); asm volatile("s_waitcnt vmcnt(0)" ::: "memory"); FA_WRITET(0); dm_lo = dn_lo; dm_hi = dn_hi;
;     __syncthreads();
;     f32x16 pA0, pA1; float mnA, alA; half8 pa0, pa1, pa2, pa3;
;     ...
;     for (int t = 0; t < NT; ++t) {
;         if (t + 1 < NT) FA_LOADT(U.j_lo + t + 1);
;         FA_SBAR();
;         FA_STEP(t);
;         FA_SBAR();
;         if (t + 1 < NT) { asm volatile("s_waitcnt vmcnt(0)" ::: "memory"); FA_WRITET((t + 1) & 1); dm_lo = dn_lo; dm_hi = dn_hi; }
;         __syncthreads();
;     }
	ds_write_b128 v228, v[146:149] offset:32768
	s_waitcnt vmcnt(10)
	ds_write_b128 v228, v[150:153] offset:40960
	v_lshlrev_b32_e64 v10, v5, 1
	v_cmp_lt_i32_e32 vcc, -1, v5
	v_lshlrev_b32_e64 v11, v6, 1
	v_lshlrev_b32_e64 v12, v4, 1
	v_cndmask_b32_e32 v5, 0, v10, vcc
	v_cmp_lt_i32_e32 vcc, -1, v6
	v_mov_b32_e32 v10, v3
	v_mov_b32_e32 v13, v3
	v_cndmask_b32_e32 v6, 0, v11, vcc
	v_cmp_lt_i32_e32 vcc, -1, v4
	v_mov_b32_e32 v11, v3
	v_mov_b32_e32 v14, v3
	v_cndmask_b32_e32 v4, 0, v12, vcc
	v_or3_b32 v227, v5, v4, v6
	v_add_u32_e32 v4, 0, v224
	s_waitcnt vmcnt(9)
	ds_write_b128 v4, v[154:157]
	v_add_u32_e32 v4, 0, v225
	s_waitcnt vmcnt(8)
	ds_write_b128 v4, v[158:161]
	v_lshlrev_b32_e32 v4, 1, v1
	v_and_b32_e32 v4, 32, v4
	v_and_b32_e32 v1, 0x70, v223
	v_and_b32_e32 v5, 0xc0, v223
	v_bitop3_b32 v231, v2, v1, 32 bitop3:0x36
	v_bitop3_b32 v232, v2, v1, 64 bitop3:0x36
	v_bitop3_b32 v233, v2, v1, s77 bitop3:0x36
	v_add_u32_e32 v1, s25, v2
	v_and_or_b32 v2, v7, s6, v4
	s_add_i32 s6, s16, 0x1ec5
	v_add3_u32 v234, v5, 0, v2
	v_add_u32_e32 v2, s6, v220
	v_sub_u32_e32 v2, v2, v222
	v_subrev_u32_e32 v235, s12, v2
	v_mov_b32_e32 v2, v3
	v_mov_b32_e32 v4, v3
	v_mov_b32_e32 v5, v3
	v_mov_b32_e32 v6, v3
	v_mov_b32_e32 v7, v3
	v_mov_b32_e32 v12, v3
	v_mov_b32_e32 v15, v3
	v_mov_b64_e32 v[32:33], v[16:17]
	v_mov_b64_e32 v[48:49], v[16:17]
	v_mov_b64_e32 v[64:65], v[16:17]
	v_mov_b64_e32 v[80:81], v[16:17]
	s_mov_b32 s22, 63
	s_mov_b32 s23, 0
	s_or_b32 s24, s17, 31
	v_lshl_add_u32 v229, v220, 8, 0
	v_cmp_gt_u32_e64 s[0:1], 32, v221
	v_lshl_add_u32 v226, v220, 2, s25
	s_ashr_i32 s25, s2, 8
	v_mov_b32_e32 v237, 0
	v_mov_b32_e32 v236, 0xf149f2ca
	s_movk_i32 s37, 0x4000
	v_mov_b64_e32 v[30:31], v[14:15]
	v_mov_b64_e32 v[28:29], v[12:13]
	v_mov_b64_e32 v[26:27], v[10:11]
	v_mov_b64_e32 v[24:25], v[8:9]
	v_mov_b64_e32 v[22:23], v[6:7]
	v_mov_b64_e32 v[20:21], v[4:5]
	v_mov_b64_e32 v[18:19], v[2:3]
	v_mov_b64_e32 v[46:47], v[14:15]
	v_mov_b64_e32 v[44:45], v[12:13]
	v_mov_b64_e32 v[42:43], v[10:11]
	v_mov_b64_e32 v[40:41], v[8:9]
	v_mov_b64_e32 v[38:39], v[6:7]
	v_mov_b64_e32 v[36:37], v[4:5]
	v_mov_b64_e32 v[34:35], v[2:3]
	v_mov_b64_e32 v[62:63], v[14:15]
	v_mov_b64_e32 v[60:61], v[12:13]
	v_mov_b64_e32 v[58:59], v[10:11]
	v_mov_b64_e32 v[56:57], v[8:9]
	v_mov_b64_e32 v[54:55], v[6:7]
	v_mov_b64_e32 v[52:53], v[4:5]
	v_mov_b64_e32 v[50:51], v[2:3]
	v_mov_b64_e32 v[78:79], v[14:15]
	v_mov_b64_e32 v[76:77], v[12:13]
	v_mov_b64_e32 v[74:75], v[10:11]
	v_mov_b64_e32 v[72:73], v[8:9]
	v_mov_b64_e32 v[70:71], v[6:7]
	v_mov_b64_e32 v[68:69], v[4:5]
	v_mov_b64_e32 v[66:67], v[2:3]
	s_branch .Lmoba_rot
.LBB0_4947:
	s_add_i32 s23, s23, 1
	s_add_i32 s22, s22, 64
	s_addk_i32 s37, 0x4000
	v_subrev_u32_e32 v235, 64, v235
.Lmoba_rot:
	s_cmp_lt_u32 s23, s15
	s_cselect_b64 s[6:7], -1, 0
	s_sub_i32 s8, s22, 63
	s_and_b32 s9, s23, 1
	v_mov_b32_e32 v2, s9
	s_cmp_gt_i32 s8, s24
	s_cselect_b64 vcc, -1, 0
	v_lshlrev_b32_e32 v2, 14, v2
	v_add_u32_e32 v4, v229, v2
	v_add_u32_e32 v16, v4, v230
	v_add_u32_e32 v17, v4, v231
	v_add_u32_e32 v102, v4, v232
	v_add_u32_e32 v103, v4, v233
	s_cmp_eq_u32 s13, s23
	s_waitcnt lgkmcnt(0)
	s_barrier
	s_cbranch_scc1 .LBB0_4964
	s_cbranch_vccnz .Lmoba_skipq
	ds_read_b128 v[4:7], v16 offset:32768
	ds_read_b128 v[8:11], v16 offset:40960
	ds_read_b128 v[12:15], v17 offset:32768
	ds_read_b128 v[82:85], v17 offset:40960
	ds_read_b128 v[86:89], v102 offset:32768
	ds_read_b128 v[90:93], v102 offset:40960
	ds_read_b128 v[94:97], v103 offset:32768
	ds_read_b128 v[98:101], v103 offset:40960
	s_and_b64 vcc, exec, s[6:7]
	s_cbranch_vccz .Lmoba_q_nold
	v_readfirstlane_b32 vcc_hi, v0
	s_and_b32 vcc_lo, s37, 0x4000
	s_lshr_b32 vcc_hi, vcc_hi, 6
	s_lshl_b32 vcc_hi, vcc_hi, 10
	s_add_i32 vcc_lo, vcc_lo, vcc_hi
	v_add_u32_e32 v114, s22, v204
	v_add_u32_e32 v116, 1, v114
	v_ashrrev_i32_e32 v117, 31, v116
	v_add_u32_e32 v120, 33, v114
	v_lshlrev_b64 v[116:117], 8, v[116:117]
	v_ashrrev_i32_e32 v121, 31, v120
	s_add_i32 m0, vcc_lo, 0x8000
	v_lshl_add_u64 v[118:119], v[206:207], 0, v[116:117]
	v_lshlrev_b64 v[120:121], 8, v[120:121]
	global_load_lds_dwordx4 v[118:119], off
	s_add_i32 m0, vcc_lo, 0xa000
	v_lshl_add_u64 v[122:123], v[206:207], 0, v[120:121]
	v_lshl_add_u64 v[116:117], v[208:209], 0, v[116:117]
	global_load_lds_dwordx4 v[122:123], off
	s_mov_b32 m0, vcc_lo
	v_lshl_add_u64 v[118:119], v[208:209], 0, v[120:121]
	s_nop 0
	global_load_lds_dwordx4 v[116:117], off
	s_add_i32 m0, vcc_lo, 0x2000
	s_nop 0
	global_load_lds_dwordx4 v[118:119], off

; template <int KIND>
; __device__ __forceinline__ void run_unit(LAS char* lds, const UnitArgs& U, int tid_in) {
;     ...
;     const int wid = __builtin_amdgcn_readfirstlane(tid >> 6), lane = tid & 63, r32 = lane & 31, hi = lane >> 5;
;     const int sr = tid >> 4, sc = (tid & 15) * 8;
;     const int qlo = U.P0 + wid * 32, rowpos = qlo + r32;
;     const float sc_ = MLA ? SC192 : SC128; const float C2 = 1.4426950408889634f * sc_;
;     LAS float* wsf = (LAS float*)(lds + OFF_WS) + wid * 96; LAS float* li_l = wsf; LAS float* al_l = wsf + 32; LAS float* g_l = wsf + 64;
;     half8 qr[MLA ? 12 : 8];
;     { const h16* qp = U.Q + (size_t)(wid * 32 + r32) * U.qld + hi * 8;
; #pragma unroll
;       for (int d0 = 0; d0 < (MLA ? 12 : 8); ++d0) qr[d0] = *(const half8*)(qp + d0 * 16); }
;     unsigned mb0 = 0, mb1 = 0, mb2 = 0, mb3 = 0;
;     if constexpr (KIND == K_MOBA) { const int* s = (const int*)U.mk + (size_t)rowpos * 16;
; #pragma unroll
;         for (int i = 0; i < 3; ++i) { const int b = s[i]; if (b >= 0) mb0 |= 1u << b; } }
;     if constexpr (KIND == K_SLC) { const u32x4 m = *(const u32x4*)((const unsigned*)U.mk + (size_t)rowpos * 4); mb0 = m[0]; mb1 = m[1]; mb2 = m[2]; mb3 = m[3]; }
;     const int nvis_row = rowpos >= 31 ? ((rowpos - 31) >> 4) + 1 : 0;
;     const int NT = U.j_hi - U.j_lo;
;     half8 st_k0, st_k1, st_v0, st_v1, st_kr; unsigned dm_lo = 0, dm_hi = 0, dn_lo = 0, dn_hi = 0;
;     const int kws = FA_KSWZ(sr, sc * 2), vst0 = v_st(sr, sc), vst1 = v_st(32 + sr, sc), krw = FA_KRSWZ(tid >> 3, (tid & 7) * 16);
;     const int vb0 = (int)(unsigned)(size_t)(lds + OFF_V) + v_rd_base(lane);
;     ...
;     float m_reg = -1e30f, l_reg = 0.f; f32x16 o[4];
; #pragma unroll
;     for (int d = 0; d < 4; ++d)
; #pragma unroll
;         for (int r = 0; r < 16; ++r) o[d][r] = 0.f;
;     FA_LOADT(U.j_lo); asm volatile("s_waitcnt vmcnt(0)" ::: "memory"); FA_WRITET(0); dm_lo = dn_lo; dm_hi = dn_hi;
; __device__ __forceinline__ void fa_mixer_phase(Frame& F, int l) {
;     ...
;         if (type == 0) {
;             U.Q = (const h16*)(ws + WS_Q192) + ((size_t)h * S + P0) * 192; U.qld = 192; U.K = (const h16*)(ws + WS_KN + (size_t)h * HEADBUF); U.KR = (const h16*)(ws + WS_BKR); U.V = (const h16*)(ws + WS_BV + (size_t)h * HEADBUF);
;             U.O = (h16*)(ws + WS_OMIX) + (size_t)P0 * DM + 512 + h * 128;
;             fa::run_unit<fa::K_MLA>(lds, U, F.tid);
.LBB0_4968:
	s_andn2_b64 vcc, exec, s[0:1]
	s_cbranch_vccnz .LBB0_4921
	s_cmp_eq_u32 s10, 1
	s_mov_b64 s[0:1], -1
	s_cbranch_scc1 .LBB0_4987
	s_lshl_b32 s0, s14, 13
	s_add_i32 s0, s0, s2
	s_mul_hi_u32 s1, s0, 0x180
	s_mulk_i32 s0, 0x180
	v_readlane_b32 s6, v252, 30
	s_add_u32 s0, s6, s0
	v_readlane_b32 s6, v252, 31
	s_addc_u32 s1, s6, s1
	s_lshl_b32 s8, s14, 21
	v_readlane_b32 s6, v252, 24
	v_mov_b32_e32 v1, v0
	s_add_u32 s6, s6, s8
	v_readlane_b32 s7, v252, 25
	s_addc_u32 s7, s7, 0
	s_waitcnt vmcnt(10)
	v_ashrrev_i32_e32 v182, 4, v1
	v_readlane_b32 s9, v252, 26
	v_lshlrev_b32_e32 v18, 3, v1
	v_add_u32_e32 v6, 32, v182
	v_ashrrev_i32_e32 v183, 31, v182
	s_add_u32 s8, s9, s8
	v_readlane_b32 s9, v252, 27
	v_and_b32_e32 v2, 0x78, v18
	v_lshlrev_b64 v[10:11], 8, v[182:183]
	v_ashrrev_i32_e32 v7, 31, v6
	s_addc_u32 s9, s9, 0
	v_lshlrev_b32_e32 v4, 1, v2
	v_lshl_add_u64 v[12:13], s[6:7], 0, v[10:11]
	v_mov_b32_e32 v5, v3
	v_lshlrev_b64 v[14:15], 8, v[6:7]
	v_ashrrev_i32_e32 v8, 3, v1
	v_lshl_add_u64 v[12:13], v[12:13], 0, v[4:5]
	v_lshl_add_u64 v[16:17], s[6:7], 0, v[14:15]
	v_lshl_add_u64 v[10:11], s[8:9], 0, v[10:11]
	v_lshl_add_u64 v[16:17], v[16:17], 0, v[4:5]
	global_load_dwordx4 v[114:117], v[12:13], off
	global_load_dwordx4 v[118:121], v[16:17], off
	v_lshl_add_u64 v[10:11], v[10:11], 0, v[4:5]
	v_lshl_add_u64 v[12:13], s[8:9], 0, v[14:15]
	v_ashrrev_i32_e32 v9, 31, v8
	v_readlane_b32 s24, v252, 10
	v_lshl_add_u64 v[12:13], v[12:13], 0, v[4:5]
	global_load_dwordx4 v[122:125], v[10:11], off
	global_load_dwordx4 v[126:129], v[12:13], off
	v_lshlrev_b64 v[10:11], 7, v[8:9]
	v_readlane_b32 s25, v252, 11
	s_waitcnt vmcnt(12)
	v_lshlrev_b32_e32 v190, 4, v1
	v_readfirstlane_b32 s10, v1
	v_lshl_add_u64 v[10:11], s[24:25], 0, v[10:11]
	v_and_b32_e32 v12, 0x70, v190
	v_mov_b32_e32 v13, v3
	s_ashr_i32 s10, s10, 6
	v_lshl_add_u64 v[10:11], v[10:11], 0, v[12:13]
	v_and_b32_e32 v191, 31, v1
	s_lshl_b32 s11, s10, 5
	global_load_dwordx4 v[178:181], v[10:11], off
	v_bfe_u32 v183, v1, 5, 1
	v_or_b32_e32 v2, s11, v191
	v_mov_b64_e32 v[10:11], s[0:1]
	s_movk_i32 s0, 0x180
	v_mad_i64_i32 v[10:11], s[0:1], v2, s0, v[10:11]
	v_lshlrev_b32_e32 v2, 4, v183
	v_lshl_add_u64 v[10:11], v[10:11], 0, v[2:3]
	global_load_dwordx4 v[130:133], v[10:11], off
	global_load_dwordx4 v[134:137], v[10:11], off offset:32
	global_load_dwordx4 v[138:141], v[10:11], off offset:64
	global_load_dwordx4 v[142:145], v[10:11], off offset:96
	global_load_dwordx4 v[146:149], v[10:11], off offset:128
	global_load_dwordx4 v[150:153], v[10:11], off offset:160
	global_load_dwordx4 v[154:157], v[10:11], off offset:192
	global_load_dwordx4 v[158:161], v[10:11], off offset:224
	global_load_dwordx4 v[162:165], v[10:11], off offset:256
	global_load_dwordx4 v[166:169], v[10:11], off offset:288
	global_load_dwordx4 v[170:173], v[10:11], off offset:320
	global_load_dwordx4 v[174:177], v[10:11], off offset:352
	v_and_b32_e32 v9, 0xfffff0, v182
	v_lshlrev_b32_e32 v10, 1, v182
	v_and_or_b32 v9, v10, 8, v9
	v_lshrrev_b32_e32 v10, 1, v182
	v_and_b32_e32 v14, 3, v182
	v_and_or_b32 v10, v10, 4, v14
	v_and_b32_e32 v14, 0xfffff0, v6
	v_lshlrev_b32_e32 v6, 1, v6
	v_lshrrev_b32_e32 v9, 1, v9
	v_bfe_u32 v11, v18, 5, 2
	v_and_or_b32 v6, v6, 8, v14
	v_or_b32_e32 v9, v9, v11
	v_lshrrev_b32_e32 v6, 1, v6
	v_lshlrev_b32_e32 v9, 9, v9
	v_lshlrev_b32_e32 v10, 6, v10
	v_or_b32_e32 v6, v6, v11
	v_xor_b32_e32 v11, v8, v1
	v_and_b32_e32 v15, 48, v4
	s_mul_i32 s17, s10, 0x180
	v_bitop3_b32 v7, v4, v1, s50 bitop3:0x78
	v_lshlrev_b32_e32 v6, 9, v6
	v_lshlrev_b32_e32 v11, 4, v11
	v_lshlrev_b32_e32 v14, 8, v182
	v_or3_b32 v204, v9, v10, v15
	v_and_b32_e32 v192, 63, v1
	s_add_i32 s17, s17, 0
	v_and_b32_e32 v11, 0x70, v11
	v_or3_b32 v205, v6, v10, v15
	v_lshlrev_b32_e32 v6, 7, v8
	v_add3_u32 v207, 0, v7, v14
	v_add_u32_e32 v7, 0, v204
	s_add_i32 s0, 0, 0x10000
	v_lshlrev_b32_e32 v1, 1, v1
	s_add_i32 s22, s17, 0x14000
	s_waitcnt vmcnt(0)
	s_waitcnt vmcnt(16)
	ds_write_b128 v207, v[114:117] offset:32768
	s_waitcnt vmcnt(15)
	ds_write_b128 v207, v[118:121] offset:40960
	v_add3_u32 v208, s0, v11, v6
	v_and_b32_e32 v6, 32, v1
	v_lshl_add_u64 v[184:185], s[6:7], 0, v[4:5]
	s_movk_i32 s6, 0x118
	s_waitcnt vmcnt(14)
	ds_write_b128 v7, v[122:125]
	v_add_u32_e32 v7, 0, v205
	s_waitcnt vmcnt(13)
; #define FA_SBAR() __builtin_amdgcn_sched_barrier(0)
; __device__ __forceinline__ int v_st(int k, int c) { const int kk = (k & ~0xC) | ((k & 4) << 1) | ((k & 8) >> 1); return ((kk >> 3) * 4 + (c >> 5)) * 512 + ((kk & 7) * 32 + (c & 31)) * 2; }
; __device__ __forceinline__ int v_rd_base(int lane) { return ((lane & 3) << 3) | (((lane >> 2) & 3) << 6) | (((lane >> 4) & 1) << 5) | (((lane >> 5) & 1) << 8); }
; #define FA_WRITET(bf) do { *(LAS half8*)(lds + OFF_K + (bf) * SHM_K + kws) = st_k0; *(LAS half8*)(lds + OFF_K + (bf) * SHM_K + kws + 32 * 256) = st_k1; \
;         *(LAS half8*)(lds + OFF_V + (bf) * SHM_V + vst0) = st_v0; *(LAS half8*)(lds + OFF_V + (bf) * SHM_V + vst1) = st_v1; \
;         if constexpr (MLA) *(LAS half8*)(lds + OFF_KR + (bf) * SHM_KR + krw) = st_kr; } while (0)
; template <int KIND>
; __device__ __forceinline__ void run_unit(LAS char* lds, const UnitArgs& U, int tid_in) {
;     ...
;     half8 st_k0, st_k1, st_v0, st_v1, st_kr; unsigned dm_lo = 0, dm_hi = 0, dn_lo = 0, dn_hi = 0;
;     const int kws = FA_KSWZ(sr, sc * 2), vst0 = v_st(sr, sc), vst1 = v_st(32 + sr, sc), krw = FA_KRSWZ(tid >> 3, (tid & 7) * 16);
;     const int vb0 = (int)(unsigned)(size_t)(lds + OFF_V) + v_rd_base(lane);
;     ...
;     float m_reg = -1e30f, l_reg = 0.f; f32x16 o[4];
; #pragma unroll
;     for (int d = 0; d < 4; ++d)
; #pragma unroll
;         for (int r = 0; r < 16; ++r) o[d][r] = 0.f;
;     FA_LOADT(U.j_lo); asm volatile("s_waitcnt vmcnt(0)" ::: "memory"); FA_WRITET(0); dm_lo = dn_lo; dm_hi = dn_hi;
;     __syncthreads();
;     f32x16 pA0, pA1; float mnA, alA; half8 pa0, pa1, pa2, pa3;
;     ...
;     for (int t = 0; t < NT; ++t) {
;         if (t + 1 < NT) FA_LOADT(U.j_lo + t + 1);
;         FA_SBAR();
;         FA_STEP(t);
;         FA_SBAR();
;         if (t + 1 < NT) { asm volatile("s_waitcnt vmcnt(0)" ::: "memory"); FA_WRITET((t + 1) & 1); dm_lo = dn_lo; dm_hi = dn_hi; }
;         __syncthreads();
	ds_write_b128 v7, v[126:129]
	v_and_b32_e32 v7, 0xc0, v190
	v_bitop3_b32 v220, v2, v190, s50 bitop3:0x78
	v_bitop3_b32 v221, v2, v12, 32 bitop3:0x36
	v_bitop3_b32 v222, v2, v12, 64 bitop3:0x36
	v_bitop3_b32 v223, v2, v12, s77 bitop3:0x36
	v_add_u32_e32 v1, s22, v2
	v_and_or_b32 v2, v18, s6, v6
	s_add_i32 s6, s11, 0x1ec5
	v_lshlrev_b32_e32 v193, 2, v183
	v_add3_u32 v225, v7, 0, v2
	v_add_u32_e32 v2, s6, v191
	v_sub_u32_e32 v2, v2, v193
	v_mov_b32_e32 v16, v3
	v_mov_b32_e32 v17, v3
	s_add_i32 s16, s11, s2
	v_lshl_add_u64 v[186:187], s[8:9], 0, v[4:5]
	v_lshl_add_u64 v[188:189], s[24:25], 0, v[12:13]
	v_subrev_u32_e32 v226, s12, v2
	v_add_u32_e32 v227, 64, v8
	v_and_b32_e32 v230, 15, v0
	v_bfe_u32 v231, v0, 4, 3
	v_xor_b32_e32 v232, v230, v231
	v_sub_u32_e32 v232, v232, v230
	v_lshlrev_b32_e32 v232, 4, v232
	v_ashrrev_i32_e32 v233, 31, v232
	v_lshl_add_u64 v[184:185], v[184:185], 0, v[232:233]
	v_and_b32_e32 v234, 7, v0
	v_bfe_u32 v235, v0, 3, 3
	v_xor_b32_e32 v236, v234, v235
	v_sub_u32_e32 v236, v236, v234
	v_lshlrev_b32_e32 v236, 4, v236
	v_ashrrev_i32_e32 v237, 31, v236
	v_lshl_add_u64 v[188:189], v[188:189], 0, v[236:237]
	v_lshrrev_b32_e32 v234, 7, v0
	v_bfe_u32 v235, v0, 2, 3
	v_lshl_or_b32 v234, v234, 3, v235
	v_and_b32_e32 v236, 4, v234
	v_lshlrev_b32_e32 v236, 1, v236
	v_and_b32_e32 v237, 8, v234
	v_lshrrev_b32_e32 v237, 1, v237
	v_and_b32_e32 v234, 0x33, v234
	v_or3_b32 v234, v234, v236, v237
	v_lshrrev_b32_e32 v235, 4, v0
	v_sub_u32_e32 v234, v234, v235
	v_lshlrev_b32_e32 v234, 8, v234
	v_bfe_u32 v235, v0, 5, 2
	v_lshlrev_b32_e32 v235, 6, v235
	v_and_b32_e32 v236, 3, v0
	v_lshl_or_b32 v235, v236, 4, v235
	v_lshlrev_b32_e32 v236, 4, v230
	v_sub_u32_e32 v235, v235, v236
	v_add_u32_e32 v234, v234, v235
	v_ashrrev_i32_e32 v235, 31, v234
	v_lshl_add_u64 v[186:187], v[186:187], 0, v[234:235]
	v_mov_b32_e32 v2, v3
	v_mov_b32_e32 v4, v3
	v_mov_b32_e32 v6, v3
	v_mov_b32_e32 v7, v3
	v_mov_b32_e32 v8, v3
	v_mov_b32_e32 v9, v3
	v_mov_b32_e32 v10, v3
	v_mov_b32_e32 v11, v3
	v_mov_b32_e32 v12, v3
	v_mov_b32_e32 v14, v3
	v_mov_b32_e32 v15, v3
	v_mov_b64_e32 v[32:33], v[16:17]
	v_mov_b64_e32 v[48:49], v[16:17]
	v_mov_b64_e32 v[64:65], v[16:17]
	v_mov_b64_e32 v[80:81], v[16:17]
	s_or_b32 s17, s16, 31
	v_lshl_add_u32 v209, v191, 8, 0
	v_lshl_add_u32 v224, v191, 7, s0
	v_cmp_gt_u32_e64 s[0:1], 32, v192
	v_lshl_add_u32 v206, v191, 2, s22
	s_mov_b32 s22, 0
	v_mov_b32_e32 v229, 0
	v_mov_b32_e32 v228, 0xf149f2ca
	v_mov_b64_e32 v[30:31], v[14:15]
	v_mov_b64_e32 v[28:29], v[12:13]
	v_mov_b64_e32 v[26:27], v[10:11]
	v_mov_b64_e32 v[24:25], v[8:9]
	v_mov_b64_e32 v[22:23], v[6:7]
	v_mov_b64_e32 v[20:21], v[4:5]
	v_mov_b64_e32 v[18:19], v[2:3]
	v_mov_b64_e32 v[46:47], v[14:15]
	v_mov_b64_e32 v[44:45], v[12:13]
	v_mov_b64_e32 v[42:43], v[10:11]
	v_mov_b64_e32 v[40:41], v[8:9]
	v_mov_b64_e32 v[38:39], v[6:7]
	v_mov_b64_e32 v[36:37], v[4:5]
	v_mov_b64_e32 v[34:35], v[2:3]
	v_mov_b64_e32 v[62:63], v[14:15]
	v_mov_b64_e32 v[60:61], v[12:13]
	v_mov_b64_e32 v[58:59], v[10:11]
	v_mov_b64_e32 v[56:57], v[8:9]
	v_mov_b64_e32 v[54:55], v[6:7]
	v_mov_b64_e32 v[52:53], v[4:5]
	v_mov_b64_e32 v[50:51], v[2:3]
	v_mov_b64_e32 v[78:79], v[14:15]
	v_mov_b64_e32 v[76:77], v[12:13]
	v_mov_b64_e32 v[74:75], v[10:11]
	v_mov_b64_e32 v[72:73], v[8:9]
	v_mov_b64_e32 v[70:71], v[6:7]
	v_mov_b64_e32 v[68:69], v[4:5]
	v_mov_b64_e32 v[66:67], v[2:3]
	s_mov_b32 s23, 0
	s_waitcnt vmcnt(12)
	ds_write_b128 v208, v[178:181]
	s_branch .Lmla_rot
.LBB0_4971:
	s_add_i32 s22, s22, 64
	v_subrev_u32_e32 v226, 64, v226
.Lmla_rot:
	s_cmp_lt_u32 s23, s15
	s_cselect_b64 s[6:7], -1, 0
	s_and_b32 s8, s23, 1
	v_mov_b32_e32 v4, s8
	s_cmp_gt_i32 s22, s17
	s_cselect_b64 vcc, -1, 0
	v_lshlrev_b32_e32 v2, 14, v4
	v_add_u32_e32 v5, v209, v2
	v_add_u32_e32 v214, v5, v220
	v_add_u32_e32 v248, v5, v221
	v_add_u32_e32 v249, v5, v222
	v_add_u32_e32 v5, v5, v223
	s_cmp_eq_u32 s13, s23
	s_waitcnt lgkmcnt(0)
	s_barrier
	s_cbranch_scc1 .LBB0_4984
	s_cbranch_vccnz .Lmla_skipq
	ds_read_b128 v[6:9], v214 offset:32768
	ds_read_b128 v[10:13], v214 offset:40960
	ds_read_b128 v[14:17], v248 offset:32768
	ds_read_b128 v[230:233], v248 offset:40960
	ds_read_b128 v[234:237], v249 offset:32768
	ds_read_b128 v[240:243], v249 offset:40960
	ds_read_b128 v[244:247], v5 offset:32768
	ds_read_b128 v[194:197], v5 offset:40960
	s_and_b64 vcc, exec, s[6:7]
	s_cbranch_vccz .Lmla_q_nold
	v_readfirstlane_b32 s9, v0
	s_add_i32 s8, s23, 1
	s_and_b32 s8, s8, 1
	s_lshr_b32 s9, s9, 6
	s_lshl_b32 s9, s9, 10
	s_lshl_b32 vcc_lo, s8, 14
	s_add_i32 vcc_lo, vcc_lo, s9
	s_lshl_b32 s8, s8, 13
	s_add_i32 s8, s8, s9
	s_add_i32 s8, s8, 0x10000
	v_add_u32_e32 v98, s22, v182
	v_add_u32_e32 v100, 64, v98
	v_ashrrev_i32_e32 v101, 31, v100
	v_add_u32_e32 v104, 0x60, v98
	v_lshlrev_b64 v[100:101], 8, v[100:101]
	v_ashrrev_i32_e32 v105, 31, v104
	s_add_i32 m0, vcc_lo, 0x8000
	v_lshl_add_u64 v[102:103], v[184:185], 0, v[100:101]
	v_lshlrev_b64 v[104:105], 8, v[104:105]
	global_load_lds_dwordx4 v[102:103], off
	s_add_i32 m0, vcc_lo, 0xa000
	v_lshl_add_u64 v[106:107], v[184:185], 0, v[104:105]
	v_lshl_add_u64 v[100:101], v[186:187], 0, v[100:101]
	global_load_lds_dwordx4 v[106:107], off
	s_mov_b32 m0, vcc_lo
	v_lshl_add_u64 v[102:103], v[186:187], 0, v[104:105]
	v_add_u32_e32 v104, s22, v227
	global_load_lds_dwordx4 v[100:101], off
	s_add_i32 m0, vcc_lo, 0x2000
	v_ashrrev_i32_e32 v105, 31, v104
	v_lshlrev_b64 v[104:105], 7, v[104:105]
	global_load_lds_dwordx4 v[102:103], off
	s_mov_b32 m0, s8
	v_lshl_add_u64 v[104:105], v[188:189], 0, v[104:105]
	global_load_lds_dwordx4 v[104:105], off

; template <int KIND>
; __device__ __forceinline__ void run_unit(LAS char* lds, const UnitArgs& U, int tid_in) {
;     ...
;     int tid = tid_in; asm volatile("" : "+v"(tid));
;     const int wid = __builtin_amdgcn_readfirstlane(tid >> 6), lane = tid & 63, r32 = lane & 31, hi = lane >> 5;
;     const int sr = tid >> 4, sc = (tid & 15) * 8;
;     const int qlo = U.P0 + wid * 32, rowpos = qlo + r32;
;     const float sc_ = MLA ? SC192 : SC128; const float C2 = 1.4426950408889634f * sc_;
;     LAS float* wsf = (LAS float*)(lds + OFF_WS) + wid * 96; LAS float* li_l = wsf; LAS float* al_l = wsf + 32; LAS float* g_l = wsf + 64;
;     half8 qr[MLA ? 12 : 8];
;     { const h16* qp = U.Q + (size_t)(wid * 32 + r32) * U.qld + hi * 8;
; #pragma unroll
;       for (int d0 = 0; d0 < (MLA ? 12 : 8); ++d0) qr[d0] = *(const half8*)(qp + d0 * 16); }
;     unsigned mb0 = 0, mb1 = 0, mb2 = 0, mb3 = 0;
;     if constexpr (KIND == K_MOBA) { const int* s = (const int*)U.mk + (size_t)rowpos * 16;
; #pragma unroll
;         for (int i = 0; i < 3; ++i) { const int b = s[i]; if (b >= 0) mb0 |= 1u << b; } }
;     if constexpr (KIND == K_SLC) { const u32x4 m = *(const u32x4*)((const unsigned*)U.mk + (size_t)rowpos * 4); mb0 = m[0]; mb1 = m[1]; mb2 = m[2]; mb3 = m[3]; }
;     const int nvis_row = rowpos >= 31 ? ((rowpos - 31) >> 4) + 1 : 0;
;     const int NT = U.j_hi - U.j_lo;
;     half8 st_k0, st_k1, st_v0, st_v1, st_kr; unsigned dm_lo = 0, dm_hi = 0, dn_lo = 0, dn_hi = 0;
;     const int kws = FA_KSWZ(sr, sc * 2), vst0 = v_st(sr, sc), vst1 = v_st(32 + sr, sc), krw = FA_KRSWZ(tid >> 3, (tid & 7) * 16);
;     const int vb0 = (int)(unsigned)(size_t)(lds + OFF_V) + v_rd_base(lane);
;     ...
;     float m_reg = -1e30f, l_reg = 0.f; f32x16 o[4];
; #pragma unroll
;     for (int d = 0; d < 4; ++d)
; #pragma unroll
;         for (int r = 0; r < 16; ++r) o[d][r] = 0.f;
;     FA_LOADT(U.j_lo); asm volatile("s_waitcnt vmcnt(0)" ::: "memory"); FA_WRITET(0); dm_lo = dn_lo; dm_hi = dn_hi;
;     __syncthreads();
; __device__ __forceinline__ void fa_mixer_phase(Frame& F, int l) {
;     ...
;             U.Q = (const h16*)(ws + WS_CQROPE + (size_t)h * HEADBUF) + (size_t)P0 * 128; U.qld = 128; U.K = (const h16*)(ws + WS_KSLC); U.V = (const h16*)(ws + WS_VSLC);
;             U.O = (h16*)(ws + WS_OMIX) + (size_t)P0 * DM + 1024 + h * 128; U.mk = ws + WS_NSAMASK; U.gate = (const float*)(ws + WS_SMALL); U.gidx = h * 3 + 1; U.epi = 2;
.LBB0_4987:
	s_and_b64 vcc, exec, s[0:1]
	s_cbranch_vccz .LBB0_4921
	v_mov_b32_e32 v1, v0
	s_lshl_b32 s0, s14, 21
	s_waitcnt vmcnt(10)
	v_ashrrev_i32_e32 v166, 4, v1
	v_readlane_b32 s1, v254, 0
	v_lshlrev_b32_e32 v14, 3, v1
	v_ashrrev_i32_e32 v167, 31, v166
	v_readlane_b32 s40, v254, 2
	s_add_u32 s6, s1, s0
	v_readlane_b32 s0, v254, 1
	v_and_b32_e32 v2, 0x78, v14
	v_lshlrev_b64 v[8:9], 8, v[166:167]
	v_readlane_b32 s41, v254, 3
	s_addc_u32 s7, s0, 0
	s_lshl_b64 s[0:1], s[2:3], 8
	v_lshlrev_b32_e32 v4, 1, v2
	v_add_u32_e32 v6, 32, v166
	v_lshl_add_u64 v[10:11], s[40:41], 0, v[8:9]
	v_mov_b32_e32 v5, v3
	v_readfirstlane_b32 s10, v1
	s_add_u32 s8, s6, s0
	v_lshl_add_u64 v[10:11], v[10:11], 0, v[4:5]
	v_ashrrev_i32_e32 v7, 31, v6
	v_readlane_b32 s38, v251, 50
	s_addc_u32 s9, s7, s1
	s_ashr_i32 s16, s10, 6
	global_load_dwordx4 v[114:117], v[10:11], off
	v_lshlrev_b64 v[10:11], 8, v[6:7]
	v_readlane_b32 s39, v251, 51
	s_lshl_b32 s17, s16, 5
	v_lshl_add_u64 v[12:13], s[40:41], 0, v[10:11]
	v_lshl_add_u64 v[8:9], s[38:39], 0, v[8:9]
	s_waitcnt vmcnt(9)
	v_and_b32_e32 v174, 31, v1
	s_add_i32 s23, s17, s2
	v_lshl_add_u64 v[12:13], v[12:13], 0, v[4:5]
	v_lshl_add_u64 v[8:9], v[8:9], 0, v[4:5]
	v_or_b32_e32 v168, s23, v174
	v_readlane_b32 s0, v253, 58
	global_load_dwordx4 v[118:121], v[12:13], off
	global_load_dwordx4 v[122:125], v[8:9], off
	v_lshl_add_u64 v[8:9], s[38:39], 0, v[10:11]
	v_ashrrev_i32_e32 v169, 31, v168
	v_readlane_b32 s1, v253, 59
	v_lshl_add_u64 v[8:9], v[8:9], 0, v[4:5]
	global_load_dwordx4 v[126:129], v[8:9], off
	v_lshl_add_u64 v[10:11], v[168:169], 4, s[0:1]
	global_load_dwordx4 v[130:133], v[10:11], off
	v_or_b32_e32 v8, s17, v174
	v_ashrrev_i32_e32 v9, 31, v8
	v_bfe_u32 v167, v1, 5, 1
	v_lshlrev_b64 v[8:9], 8, v[8:9]
	v_lshlrev_b32_e32 v2, 4, v167
	v_lshl_add_u64 v[8:9], s[8:9], 0, v[8:9]
	v_lshl_add_u64 v[8:9], v[8:9], 0, v[2:3]
	global_load_dwordx4 v[134:137], v[8:9], off
	global_load_dwordx4 v[138:141], v[8:9], off offset:32
	global_load_dwordx4 v[142:145], v[8:9], off offset:64
	global_load_dwordx4 v[146:149], v[8:9], off offset:96
	global_load_dwordx4 v[150:153], v[8:9], off offset:128
	global_load_dwordx4 v[154:157], v[8:9], off offset:160
	global_load_dwordx4 v[158:161], v[8:9], off offset:192
	global_load_dwordx4 v[162:165], v[8:9], off offset:224
	v_and_b32_e32 v7, 0xfffff0, v166
	v_lshlrev_b32_e32 v12, 1, v166
	v_and_or_b32 v7, v12, 8, v7
	v_and_b32_e32 v11, 0xfffff0, v6
	v_lshlrev_b32_e32 v6, 1, v6
	v_lshrrev_b32_e32 v13, 1, v166
	v_bfe_u32 v8, v14, 5, 2
	v_and_b32_e32 v9, 3, v166
	v_lshrrev_b32_e32 v7, 1, v7
	v_and_or_b32 v6, v6, 8, v11
	v_and_or_b32 v9, v13, 4, v9
	v_or_b32_e32 v7, v7, v8
	v_lshrrev_b32_e32 v6, 1, v6
	v_lshlrev_b32_e32 v9, 6, v9
	v_and_b32_e32 v11, 48, v4
	v_lshlrev_b32_e32 v7, 9, v7
	v_or_b32_e32 v6, v6, v8
	v_lshlrev_b32_e32 v10, 8, v166
	s_mul_i32 s0, s16, 0x180
	v_bitop3_b32 v12, v4, v1, s50 bitop3:0x78
	v_lshlrev_b32_e32 v6, 9, v6
	v_or3_b32 v180, v7, v9, v11
	s_add_i32 s0, s0, 0
	v_add3_u32 v179, 0, v12, v10
	v_or3_b32 v181, v6, v9, v11
	v_add_u32_e32 v6, 0, v180
	v_lshlrev_b32_e32 v177, 4, v1
	v_and_b32_e32 v176, 63, v1
	s_add_i32 s6, s0, 0x14000
	v_add_u32_e32 v7, 0, v181
	s_waitcnt vmcnt(0)
	v_lshl_add_u32 v178, v174, 2, s6
	v_bitop3_b32 v183, v2, v177, s50 bitop3:0x78
	v_lshlrev_b32_e32 v175, 2, v167
	v_mov_b32_e32 v16, v3
	s_waitcnt vmcnt(12)
	ds_write_b128 v179, v[114:117] offset:32768
	s_waitcnt vmcnt(11)
	ds_write_b128 v179, v[118:121] offset:40960
	s_waitcnt vmcnt(10)
	ds_write_b128 v6, v[122:125]
	s_waitcnt vmcnt(9)
	ds_write_b128 v7, v[126:129]
	v_lshlrev_b32_e32 v6, 1, v1
	v_and_b32_e32 v1, 0x70, v177
	v_and_b32_e32 v6, 32, v6
	v_bitop3_b32 v184, v2, v1, 32 bitop3:0x36
	v_bitop3_b32 v185, v2, v1, 64 bitop3:0x36
	v_bitop3_b32 v186, v2, v1, s77 bitop3:0x36
	v_add_u32_e32 v1, s6, v2
	s_movk_i32 s6, 0x118
	v_and_b32_e32 v7, 0xc0, v177
	v_and_or_b32 v2, v14, s6, v6
	s_add_i32 s6, s17, 0x1ec5
	v_add3_u32 v187, v7, 0, v2
	v_add_u32_e32 v2, s6, v174
	v_sub_u32_e32 v2, v2, v175
	v_mov_b32_e32 v17, v3
	v_lshl_add_u64 v[170:171], s[40:41], 0, v[4:5]
	v_lshl_add_u64 v[172:173], s[38:39], 0, v[4:5]
	v_and_b32_e32 v98, 15, v0
	v_bfe_u32 v99, v0, 4, 3
	v_xor_b32_e32 v100, v98, v99
	v_sub_u32_e32 v100, v100, v98
	v_lshlrev_b32_e32 v100, 4, v100
	v_ashrrev_i32_e32 v101, 31, v100
	v_lshl_add_u64 v[170:171], v[170:171], 0, v[100:101]
	v_lshrrev_b32_e32 v102, 7, v0
	v_bfe_u32 v103, v0, 2, 3
	v_lshl_or_b32 v102, v102, 3, v103
	v_and_b32_e32 v104, 4, v102
	v_lshlrev_b32_e32 v104, 1, v104
	v_and_b32_e32 v105, 8, v102
	v_lshrrev_b32_e32 v105, 1, v105
	v_and_b32_e32 v102, 0x33, v102
	v_or3_b32 v102, v102, v104, v105
	v_lshrrev_b32_e32 v103, 4, v0
	v_sub_u32_e32 v102, v102, v103
	v_lshlrev_b32_e32 v102, 8, v102
	v_bfe_u32 v103, v0, 5, 2
	v_lshlrev_b32_e32 v103, 6, v103
	v_and_b32_e32 v104, 3, v0
	v_lshl_or_b32 v103, v104, 4, v103
	v_lshlrev_b32_e32 v104, 4, v98
	v_sub_u32_e32 v103, v103, v104
	v_add_u32_e32 v102, v102, v103
	v_ashrrev_i32_e32 v103, 31, v102
	v_lshl_add_u64 v[172:173], v[172:173], 0, v[102:103]
	v_subrev_u32_e32 v188, s12, v2
	v_mov_b32_e32 v2, v3
	v_mov_b32_e32 v4, v3
	v_mov_b32_e32 v6, v3
	v_mov_b32_e32 v7, v3
	v_mov_b32_e32 v8, v3
	v_mov_b32_e32 v9, v3
	v_mov_b32_e32 v10, v3
	v_mov_b32_e32 v11, v3
	v_mov_b32_e32 v12, v3
	v_mov_b32_e32 v13, v3
	v_mov_b32_e32 v14, v3
	v_mov_b32_e32 v15, v3
	v_mov_b64_e32 v[32:33], v[16:17]
	v_mov_b64_e32 v[48:49], v[16:17]
	v_mov_b64_e32 v[64:65], v[16:17]
	v_mov_b64_e32 v[80:81], v[16:17]
	s_mov_b32 s22, 63
	s_or_b32 s24, s23, 31
	v_lshl_add_u32 v182, v174, 8, 0
	v_cmp_gt_u32_e64 s[0:1], 32, v176
	s_mov_b32 s25, 0
	v_mov_b32_e32 v190, 0
	v_mov_b32_e32 v189, 0xf149f2ca
	s_movk_i32 s37, 0x4000
	v_mov_b64_e32 v[30:31], v[14:15]
	v_mov_b64_e32 v[28:29], v[12:13]
	v_mov_b64_e32 v[26:27], v[10:11]
	v_mov_b64_e32 v[24:25], v[8:9]
	v_mov_b64_e32 v[22:23], v[6:7]
	v_mov_b64_e32 v[20:21], v[4:5]
	v_mov_b64_e32 v[18:19], v[2:3]
	v_mov_b64_e32 v[46:47], v[14:15]
	v_mov_b64_e32 v[44:45], v[12:13]
	v_mov_b64_e32 v[42:43], v[10:11]
	v_mov_b64_e32 v[40:41], v[8:9]
	v_mov_b64_e32 v[38:39], v[6:7]
	v_mov_b64_e32 v[36:37], v[4:5]
	v_mov_b64_e32 v[34:35], v[2:3]
	v_mov_b64_e32 v[62:63], v[14:15]
	v_mov_b64_e32 v[60:61], v[12:13]
	v_mov_b64_e32 v[58:59], v[10:11]
	v_mov_b64_e32 v[56:57], v[8:9]
	v_mov_b64_e32 v[54:55], v[6:7]
	v_mov_b64_e32 v[52:53], v[4:5]
	v_mov_b64_e32 v[50:51], v[2:3]
	v_mov_b64_e32 v[78:79], v[14:15]
	v_mov_b64_e32 v[76:77], v[12:13]
	v_mov_b64_e32 v[74:75], v[10:11]
	v_mov_b64_e32 v[72:73], v[8:9]
	v_mov_b64_e32 v[70:71], v[6:7]
	v_mov_b64_e32 v[68:69], v[4:5]
	v_mov_b64_e32 v[66:67], v[2:3]
	s_branch .Lslc_rot
; #define FA_SBAR() __builtin_amdgcn_sched_barrier(0)
; #define FA_WRITET(bf) do { *(LAS half8*)(lds + OFF_K + (bf) * SHM_K + kws) = st_k0; *(LAS half8*)(lds + OFF_K + (bf) * SHM_K + kws + 32 * 256) = st_k1; \
;         *(LAS half8*)(lds + OFF_V + (bf) * SHM_V + vst0) = st_v0; *(LAS half8*)(lds + OFF_V + (bf) * SHM_V + vst1) = st_v1; \
;         if constexpr (MLA) *(LAS half8*)(lds + OFF_KR + (bf) * SHM_KR + krw) = st_kr; } while (0)
; template <int KIND>
; __device__ __forceinline__ void run_unit(LAS char* lds, const UnitArgs& U, int tid_in) {
;     ...
;     for (int t = 0; t < NT; ++t) {
;         if (t + 1 < NT) FA_LOADT(U.j_lo + t + 1);
;         FA_SBAR();
;         FA_STEP(t);
;         FA_SBAR();
;         if (t + 1 < NT) { asm volatile("s_waitcnt vmcnt(0)" ::: "memory"); FA_WRITET((t + 1) & 1); dm_lo = dn_lo; dm_hi = dn_hi; }
;         __syncthreads();
.LBB0_4989:
	s_add_i32 s25, s25, 1
	s_add_i32 s22, s22, 64
	s_addk_i32 s37, 0x4000
	v_subrev_u32_e32 v188, 64, v188
.Lslc_rot:
	s_cmp_lt_u32 s25, s15
	s_cselect_b64 s[6:7], -1, 0
	s_sub_i32 s10, s22, 63
	s_and_b32 s11, s25, 1
	v_mov_b32_e32 v2, s11
	s_cmp_gt_i32 s10, s24
	s_cselect_b64 vcc, -1, 0
	v_lshlrev_b32_e32 v2, 14, v2
	v_add_u32_e32 v4, v182, v2
	v_add_u32_e32 v16, v4, v183
	v_add_u32_e32 v17, v4, v184
	v_add_u32_e32 v191, v4, v185
	v_add_u32_e32 v196, v4, v186
	s_cmp_eq_u32 s13, s25
	s_waitcnt lgkmcnt(0)
	s_barrier
	s_cbranch_scc1 .LBB0_5002
	s_cbranch_vccnz .Lslc_skipq
	ds_read_b128 v[4:7], v16 offset:32768
	ds_read_b128 v[8:11], v16 offset:40960
	ds_read_b128 v[12:15], v17 offset:32768
	ds_read_b128 v[192:195], v17 offset:40960
	ds_read_b128 v[204:207], v191 offset:32768
	ds_read_b128 v[220:223], v191 offset:40960
	ds_read_b128 v[224:227], v196 offset:32768
	ds_read_b128 v[228:231], v196 offset:40960
	s_and_b64 vcc, exec, s[6:7]
	s_cbranch_vccz .Lslc_q_nold
	v_readfirstlane_b32 vcc_hi, v0
	s_and_b32 vcc_lo, s37, 0x4000
	s_lshr_b32 vcc_hi, vcc_hi, 6
	s_lshl_b32 vcc_hi, vcc_hi, 10
	s_add_i32 vcc_lo, vcc_lo, vcc_hi
	v_add_u32_e32 v98, s22, v166
	v_add_u32_e32 v100, 1, v98
	v_ashrrev_i32_e32 v101, 31, v100
	v_add_u32_e32 v104, 33, v98
	v_lshlrev_b64 v[100:101], 8, v[100:101]
	v_ashrrev_i32_e32 v105, 31, v104
	s_add_i32 m0, vcc_lo, 0x8000
	v_lshl_add_u64 v[102:103], v[170:171], 0, v[100:101]
	v_lshlrev_b64 v[104:105], 8, v[104:105]
	global_load_lds_dwordx4 v[102:103], off
	s_add_i32 m0, vcc_lo, 0xa000
	v_lshl_add_u64 v[106:107], v[170:171], 0, v[104:105]
	v_lshl_add_u64 v[100:101], v[172:173], 0, v[100:101]
	global_load_lds_dwordx4 v[106:107], off
	s_mov_b32 m0, vcc_lo
	v_lshl_add_u64 v[102:103], v[172:173], 0, v[104:105]
	s_nop 0
	global_load_lds_dwordx4 v[100:101], off
	s_add_i32 m0, vcc_lo, 0x2000
	s_nop 0
	global_load_lds_dwordx4 v[102:103], off
